# MLA: exp2 / row-sum / bf16 pack of each 16-key group issued in the shadow of the previous group's PV MFMAs (on top of v9)
# speedup vs baseline: 1.0429x; 1.0012x over previous
; #define MFMA32(a, b, c) __builtin_amdgcn_mfma_f32_32x32x16_bf16((a), (b), (c), 0, 0, 0)
; __device__ __forceinline__ void mla_attn_phase(const Ctx&, unsigned char* ws) { const Ctx c = mk_ctx();
;     ...
; #pragma unroll
;                 for (int i = 0; i < 16; ++i) { p0[i] = __builtin_amdgcn_exp2f(p0[i] - mnew); p1[i] = __builtin_amdgcn_exp2f(p1[i] - mnew); ls += p0[i] + p1[i]; }
;                 lrun = lrun * alpha + ls;
; #pragma unroll
;                 for (int i = 0; i < 16; ++i) if (grow) { oa[0][i] *= alpha; oa[1][i] *= alpha; }
;                 bf16x8 pa[4]; pa[0] = pack8(p0, 0); pa[1] = pack8(p0, 1); pa[2] = pack8(p1, 0); pa[3] = pack8(p1, 1);
; #pragma unroll
;                 for (int db = 0; db < 2; ++db)
; #pragma unroll
;                     for (int ks = 0; ks < 4; ++ks) { const bf16* vp = Vb + (32 * db + r) * VLD + 16 * ks + 4 * hi; oa[db] = MFMA32(cat4(*(const v2u*)vp, *(const v2u*)(vp + 8)), pa[ks], oa[db]); }
.Lmla_fast:
	v_exp_f32_e32 v50, v50
	v_exp_f32_e32 v51, v51
	v_exp_f32_e32 v52, v52
	v_exp_f32_e32 v53, v53
	v_exp_f32_e32 v54, v54
	v_exp_f32_e32 v55, v55
	v_exp_f32_e32 v56, v56
	v_exp_f32_e32 v57, v57
	v_pk_add_f32 v[242:243], v[50:51], v[52:53]
	s_nop 0
	v_pk_add_f32 v[242:243], v[242:243], v[54:55]
	s_nop 0
	v_pk_add_f32 v[242:243], v[242:243], v[56:57]
	v_cvt_pk_bf16_f32 v50, v50, v51
	v_cvt_pk_bf16_f32 v51, v52, v53
	v_cvt_pk_bf16_f32 v52, v54, v55
	v_cvt_pk_bf16_f32 v53, v56, v57
	s_waitcnt lgkmcnt(0)
	s_nop 1
	v_mfma_f32_32x32x16_bf16 v[18:33], v[226:229], v[50:53], v[18:33]
	v_exp_f32_e32 v58, v58
	v_exp_f32_e32 v59, v59
	v_exp_f32_e32 v60, v60
	v_exp_f32_e32 v61, v61
	v_mfma_f32_32x32x16_bf16 v[2:17], v[190:193], v[50:53], v[2:17]
	v_exp_f32_e32 v62, v62
	v_exp_f32_e32 v63, v63
	v_exp_f32_e32 v64, v64
	v_exp_f32_e32 v65, v65
	v_pk_add_f32 v[242:243], v[242:243], v[58:59]
	s_nop 0
	v_pk_add_f32 v[242:243], v[242:243], v[60:61]
	v_cvt_pk_bf16_f32 v54, v58, v59
	v_pk_add_f32 v[242:243], v[242:243], v[62:63]
	v_cvt_pk_bf16_f32 v55, v60, v61
	v_pk_add_f32 v[242:243], v[242:243], v[64:65]
	v_cvt_pk_bf16_f32 v56, v62, v63
	v_cvt_pk_bf16_f32 v57, v64, v65
	s_nop 1
	v_mfma_f32_32x32x16_bf16 v[18:33], v[230:233], v[54:57], v[18:33]
	v_exp_f32_e32 v34, v34
	v_exp_f32_e32 v35, v35
	v_exp_f32_e32 v36, v36
	v_exp_f32_e32 v37, v37
	v_mfma_f32_32x32x16_bf16 v[2:17], v[214:217], v[54:57], v[2:17]
	v_exp_f32_e32 v38, v38
	v_exp_f32_e32 v39, v39
	v_exp_f32_e32 v40, v40
	v_exp_f32_e32 v41, v41
	v_pk_add_f32 v[242:243], v[242:243], v[34:35]
	s_nop 0
	v_pk_add_f32 v[242:243], v[242:243], v[36:37]
	v_cvt_pk_bf16_f32 v34, v34, v35
	v_pk_add_f32 v[242:243], v[242:243], v[38:39]
	v_cvt_pk_bf16_f32 v35, v36, v37
	v_pk_add_f32 v[242:243], v[242:243], v[40:41]
	v_cvt_pk_bf16_f32 v36, v38, v39
	v_cvt_pk_bf16_f32 v37, v40, v41
	s_nop 1
	v_mfma_f32_32x32x16_bf16 v[18:33], v[234:237], v[34:37], v[18:33]
	v_exp_f32_e32 v42, v42
	v_exp_f32_e32 v43, v43
	v_exp_f32_e32 v44, v44
	v_exp_f32_e32 v45, v45
	v_mfma_f32_32x32x16_bf16 v[2:17], v[218:221], v[34:37], v[2:17]
	v_exp_f32_e32 v46, v46
	v_exp_f32_e32 v47, v47
	v_exp_f32_e32 v48, v48
	v_exp_f32_e32 v49, v49
	v_pk_add_f32 v[242:243], v[242:243], v[42:43]
	s_nop 0
	v_pk_add_f32 v[242:243], v[242:243], v[44:45]
	v_cvt_pk_bf16_f32 v38, v42, v43
	v_pk_add_f32 v[242:243], v[242:243], v[46:47]
	v_cvt_pk_bf16_f32 v39, v44, v45
	v_pk_add_f32 v[242:243], v[242:243], v[48:49]
	v_cvt_pk_bf16_f32 v40, v46, v47
	v_cvt_pk_bf16_f32 v41, v48, v49
	s_nop 1
	v_mfma_f32_32x32x16_bf16 v[18:33], v[238:241], v[38:41], v[18:33]
	v_mfma_f32_32x32x16_bf16 v[2:17], v[222:225], v[38:41], v[2:17]
	v_add_f32_e32 v242, v242, v243
	s_nop 0
	v_add_f32_e32 v188, v188, v242
